# scan-wave loop rewritten by hand: transposed DPP y-reduction, bank-aware registers, grouped LDS waits (same f32 math)
# baseline (speedup 1.0000x reference)
.LBB0_219:
	s_and_b64 vcc, exec, s[14:15]
	s_cbranch_vccz .LBB0_189
	s_mov_b32 s20, s13
	v_lshl_or_b32 v4, s13, 4, v137
	v_lshrrev_b32_e32 v5, 6, v173
	v_xor_b32_e32 v5, 1, v5
	v_lshlrev_b32_e32 v5, 8, v5
	v_add_u32_e32 v5, v5, v4
	v_add_u32_e32 v5, 0x15000, v5
	v_mov_b32_e32 v0, 0
	v_mov_b32_e32 v1, 0
	v_mov_b32_e32 v2, 0
	v_mov_b32_e32 v3, 0
	s_mov_b32 s13, 0
.Lscan_chunk:
	s_and_b32 s14, s13, 1
	s_mul_i32 s15, s14, 0xa800
	s_lshl_b32 s14, s14, 11
	v_add_u32_e32 v7, s15, v173
	v_add_u32_e32 v8, s15, v4
	v_add_u32_e32 v6, s14, v5
	s_waitcnt lgkmcnt(0)
	s_barrier
	ds_read_b128 v[24:27], v7 offset:768
	ds_read_b128 v[16:19], v7 offset:256
	ds_read_b128 v[20:23], v7 offset:512
	ds_read_b32 v34, v8 offset:1280
	ds_read_b128 v[28:31], v7 offset:1024
	ds_read_b128 v[12:15], v7 offset:0
	ds_read_b128 v[48:51], v7 offset:2112
	ds_read_b128 v[40:43], v7 offset:1600
	ds_read_b128 v[44:47], v7 offset:1856
	ds_read_b32 v58, v8 offset:2624
	ds_read_b128 v[52:55], v7 offset:2368
	ds_read_b128 v[36:39], v7 offset:1344
	ds_read_b128 v[72:75], v7 offset:3456
	ds_read_b128 v[64:67], v7 offset:2944
	s_waitcnt lgkmcnt(8)
	ds_read_b128 v[68:71], v7 offset:3200
	ds_read_b32 v82, v8 offset:3968
	ds_read_b128 v[76:79], v7 offset:3712
	ds_read_b128 v[60:63], v7 offset:2688
	v_pk_mul_f32 v[84:85], v[24:25], v[2:3]
	v_pk_fma_f32 v[84:85], v[26:27], v[0:1], v[84:85]
	ds_read_b128 v[24:27], v7 offset:4800
	v_add_f32_e32 v86, v84, v85
	v_pk_mul_f32 v[88:89], v[16:17], v[2:3]
	v_pk_mul_f32 v[92:93], v[18:19], v[0:1]
	v_add_f32_dpp v86, v86, v86 row_ror:8 row_mask:0xf bank_mask:0xf bound_ctrl:1
	ds_read_b128 v[16:19], v7 offset:4288
	v_pk_fma_f32 v[88:89], v[20:21], v[34:35], v[88:89] op_sel_hi:[1,0,1]
	v_add_f32_dpp v86, v86, v86 row_ror:4 row_mask:0xf bank_mask:0xf bound_ctrl:1
	v_pk_fma_f32 v[92:93], v[22:23], v[34:35], v[92:93] op_sel_hi:[1,0,1]
	s_waitcnt lgkmcnt(8)
	ds_read_b128 v[20:23], v7 offset:4544
	v_add_f32_dpp v86, v86, v86 row_ror:2 row_mask:0xf bank_mask:0xf bound_ctrl:1
	ds_read_b32 v34, v8 offset:5312
	s_nop 0
	v_add_f32_dpp v86, v86, v86 row_ror:1 row_mask:0xf bank_mask:0xf bound_ctrl:1
	v_pk_fma_f32 v[2:3], v[28:29], v[86:87], v[88:89] op_sel_hi:[1,0,1]
	v_pk_fma_f32 v[0:1], v[30:31], v[86:87], v[92:93] op_sel_hi:[1,0,1]
	v_pk_mul_f32 v[84:85], v[48:49], v[2:3]
	v_pk_mul_f32 v[88:89], v[40:41], v[2:3]
	v_pk_fma_f32 v[84:85], v[50:51], v[0:1], v[84:85]
	v_pk_mul_f32 v[92:93], v[42:43], v[0:1]
	v_add_f32_e32 v86, v84, v85
	v_pk_fma_f32 v[88:89], v[44:45], v[58:59], v[88:89] op_sel_hi:[1,0,1]
	v_pk_mul_f32 v[90:91], v[12:13], v[2:3]
	v_add_f32_dpp v86, v86, v86 row_ror:8 row_mask:0xf bank_mask:0xf bound_ctrl:1
	v_pk_fma_f32 v[92:93], v[46:47], v[58:59], v[92:93] op_sel_hi:[1,0,1]
	v_pk_fma_f32 v[90:91], v[14:15], v[0:1], v[90:91]
	v_add_f32_dpp v86, v86, v86 row_ror:4 row_mask:0xf bank_mask:0xf bound_ctrl:1
	ds_read_b128 v[28:31], v7 offset:5056
	ds_read_b128 v[12:15], v7 offset:4032
	v_add_f32_dpp v86, v86, v86 row_ror:2 row_mask:0xf bank_mask:0xf bound_ctrl:1
	v_add_f32_e32 v96, v90, v91
	ds_read_b128 v[48:51], v7 offset:6144
	v_add_f32_dpp v86, v86, v86 row_ror:1 row_mask:0xf bank_mask:0xf bound_ctrl:1
	ds_read_b128 v[40:43], v7 offset:5632
	v_pk_fma_f32 v[2:3], v[52:53], v[86:87], v[88:89] op_sel_hi:[1,0,1]
	v_pk_fma_f32 v[0:1], v[54:55], v[86:87], v[92:93] op_sel_hi:[1,0,1]
	s_waitcnt lgkmcnt(8)
	v_pk_mul_f32 v[84:85], v[72:73], v[2:3]
	v_pk_mul_f32 v[88:89], v[64:65], v[2:3]
	v_pk_fma_f32 v[84:85], v[74:75], v[0:1], v[84:85]
	v_pk_mul_f32 v[92:93], v[66:67], v[0:1]
	v_add_f32_e32 v86, v84, v85
	v_pk_fma_f32 v[88:89], v[68:69], v[82:83], v[88:89] op_sel_hi:[1,0,1]
	v_pk_mul_f32 v[90:91], v[36:37], v[2:3]
	v_add_f32_dpp v86, v86, v86 row_ror:8 row_mask:0xf bank_mask:0xf bound_ctrl:1
	v_pk_fma_f32 v[92:93], v[70:71], v[82:83], v[92:93] op_sel_hi:[1,0,1]
	v_pk_fma_f32 v[90:91], v[38:39], v[0:1], v[90:91]
	v_add_f32_dpp v86, v86, v86 row_ror:4 row_mask:0xf bank_mask:0xf bound_ctrl:1
	ds_read_b128 v[44:47], v7 offset:5888
	ds_read_b32 v58, v8 offset:6656
	v_add_f32_dpp v86, v86, v86 row_ror:2 row_mask:0xf bank_mask:0xf bound_ctrl:1
	ds_read_b128 v[52:55], v7 offset:6400
	ds_read_b128 v[36:39], v7 offset:5376
	v_add_f32_dpp v86, v86, v86 row_ror:1 row_mask:0xf bank_mask:0xf bound_ctrl:1
	v_add_f32_e32 v97, v90, v91
	v_pk_fma_f32 v[2:3], v[76:77], v[86:87], v[88:89] op_sel_hi:[1,0,1]
	v_pk_fma_f32 v[0:1], v[78:79], v[86:87], v[92:93] op_sel_hi:[1,0,1]
	s_waitcnt lgkmcnt(6)
	v_pk_mul_f32 v[84:85], v[24:25], v[2:3]
	v_pk_mul_f32 v[88:89], v[16:17], v[2:3]
	v_pk_fma_f32 v[84:85], v[26:27], v[0:1], v[84:85]
	v_pk_mul_f32 v[92:93], v[18:19], v[0:1]
	v_add_f32_e32 v86, v84, v85
	v_pk_fma_f32 v[88:89], v[20:21], v[34:35], v[88:89] op_sel_hi:[1,0,1]
	ds_read_b128 v[72:75], v7 offset:7488
	v_add_f32_dpp v86, v86, v86 row_ror:8 row_mask:0xf bank_mask:0xf bound_ctrl:1
	v_pk_mul_f32 v[90:91], v[60:61], v[2:3]
	v_pk_fma_f32 v[92:93], v[22:23], v[34:35], v[92:93] op_sel_hi:[1,0,1]
	v_add_f32_dpp v86, v86, v86 row_ror:4 row_mask:0xf bank_mask:0xf bound_ctrl:1
	v_pk_fma_f32 v[90:91], v[62:63], v[0:1], v[90:91]
	ds_read_b128 v[64:67], v7 offset:6976
	v_add_f32_dpp v86, v86, v86 row_ror:2 row_mask:0xf bank_mask:0xf bound_ctrl:1
	ds_read_b128 v[68:71], v7 offset:7232
	ds_read_b32 v82, v8 offset:8000
	v_add_f32_dpp v86, v86, v86 row_ror:1 row_mask:0xf bank_mask:0xf bound_ctrl:1
	ds_read_b128 v[76:79], v7 offset:7744
	v_pk_fma_f32 v[2:3], v[28:29], v[86:87], v[88:89] op_sel_hi:[1,0,1]
	v_pk_fma_f32 v[0:1], v[30:31], v[86:87], v[92:93] op_sel_hi:[1,0,1]
	s_waitcnt lgkmcnt(5)
	v_pk_mul_f32 v[84:85], v[48:49], v[2:3]
	v_pk_mul_f32 v[88:89], v[40:41], v[2:3]
	v_pk_fma_f32 v[84:85], v[50:51], v[0:1], v[84:85]
	ds_read_b128 v[60:63], v7 offset:6720
	v_add_f32_e32 v86, v84, v85
	v_add_f32_e32 v98, v90, v91
	v_pk_mul_f32 v[92:93], v[42:43], v[0:1]
	v_add_f32_dpp v86, v86, v86 row_ror:8 row_mask:0xf bank_mask:0xf bound_ctrl:1
	v_pk_fma_f32 v[88:89], v[44:45], v[58:59], v[88:89] op_sel_hi:[1,0,1]
	ds_read_b128 v[24:27], v7 offset:8832
	v_add_f32_dpp v86, v86, v86 row_ror:4 row_mask:0xf bank_mask:0xf bound_ctrl:1
	v_pk_mul_f32 v[90:91], v[12:13], v[2:3]
	v_pk_fma_f32 v[92:93], v[46:47], v[58:59], v[92:93] op_sel_hi:[1,0,1]
	v_add_f32_dpp v86, v86, v86 row_ror:2 row_mask:0xf bank_mask:0xf bound_ctrl:1
	v_pk_fma_f32 v[90:91], v[14:15], v[0:1], v[90:91]
	ds_read_b128 v[16:19], v7 offset:8320
	v_add_f32_dpp v86, v86, v86 row_ror:1 row_mask:0xf bank_mask:0xf bound_ctrl:1
	ds_read_b128 v[20:23], v7 offset:8576
	v_pk_fma_f32 v[2:3], v[52:53], v[86:87], v[88:89] op_sel_hi:[1,0,1]
	v_pk_fma_f32 v[0:1], v[54:55], v[86:87], v[92:93] op_sel_hi:[1,0,1]
	s_waitcnt lgkmcnt(3)
	v_pk_mul_f32 v[84:85], v[72:73], v[2:3]
	ds_read_b32 v34, v8 offset:9344
	v_pk_fma_f32 v[84:85], v[74:75], v[0:1], v[84:85]
	ds_read_b128 v[28:31], v7 offset:9088
	v_add_f32_e32 v86, v84, v85
	v_pk_mul_f32 v[88:89], v[64:65], v[2:3]
	ds_read_b128 v[12:15], v7 offset:8064
	v_add_f32_dpp v86, v86, v86 row_ror:8 row_mask:0xf bank_mask:0xf bound_ctrl:1
	v_add_f32_e32 v99, v90, v91
	v_pk_mul_f32 v[92:93], v[66:67], v[0:1]
	v_add_f32_dpp v86, v86, v86 row_ror:4 row_mask:0xf bank_mask:0xf bound_ctrl:1
	v_pk_fma_f32 v[88:89], v[68:69], v[82:83], v[88:89] op_sel_hi:[1,0,1]
	ds_read_b128 v[48:51], v7 offset:10176
	v_add_f32_dpp v86, v86, v86 row_ror:2 row_mask:0xf bank_mask:0xf bound_ctrl:1
	v_pk_mul_f32 v[90:91], v[36:37], v[2:3]
	v_pk_fma_f32 v[92:93], v[70:71], v[82:83], v[92:93] op_sel_hi:[1,0,1]
	v_add_f32_dpp v86, v86, v86 row_ror:1 row_mask:0xf bank_mask:0xf bound_ctrl:1
	v_pk_fma_f32 v[90:91], v[38:39], v[0:1], v[90:91]
	v_pk_fma_f32 v[2:3], v[76:77], v[86:87], v[88:89] op_sel_hi:[1,0,1]
	v_pk_fma_f32 v[0:1], v[78:79], v[86:87], v[92:93] op_sel_hi:[1,0,1]
	s_waitcnt lgkmcnt(1)
	v_pk_mul_f32 v[84:85], v[24:25], v[2:3]
	ds_read_b128 v[40:43], v7 offset:9664
	v_pk_fma_f32 v[84:85], v[26:27], v[0:1], v[84:85]
	ds_read_b128 v[44:47], v7 offset:9920
	v_add_f32_e32 v86, v84, v85
	ds_read_b32 v58, v8 offset:10688
	ds_read_b128 v[52:55], v7 offset:10432
	v_add_f32_dpp v86, v86, v86 row_ror:8 row_mask:0xf bank_mask:0xf bound_ctrl:1
	v_pk_mul_f32 v[88:89], v[16:17], v[2:3]
	ds_read_b128 v[36:39], v7 offset:9408
	v_add_f32_dpp v86, v86, v86 row_ror:4 row_mask:0xf bank_mask:0xf bound_ctrl:1
	v_add_f32_e32 v100, v90, v91
	v_pk_mul_f32 v[92:93], v[18:19], v[0:1]
	v_add_f32_dpp v86, v86, v86 row_ror:2 row_mask:0xf bank_mask:0xf bound_ctrl:1
	v_pk_fma_f32 v[88:89], v[20:21], v[34:35], v[88:89] op_sel_hi:[1,0,1]
	ds_read_b128 v[72:75], v7 offset:11520
	v_add_f32_dpp v86, v86, v86 row_ror:1 row_mask:0xf bank_mask:0xf bound_ctrl:1
	v_pk_mul_f32 v[90:91], v[60:61], v[2:3]
	v_pk_fma_f32 v[92:93], v[22:23], v[34:35], v[92:93] op_sel_hi:[1,0,1]
	v_pk_fma_f32 v[2:3], v[28:29], v[86:87], v[88:89] op_sel_hi:[1,0,1]
	v_pk_fma_f32 v[90:91], v[62:63], v[0:1], v[90:91]
	v_pk_fma_f32 v[0:1], v[30:31], v[86:87], v[92:93] op_sel_hi:[1,0,1]
	s_waitcnt lgkmcnt(1)
	v_pk_mul_f32 v[84:85], v[48:49], v[2:3]
	ds_read_b128 v[64:67], v7 offset:11008
	v_pk_fma_f32 v[84:85], v[50:51], v[0:1], v[84:85]
	ds_read_b128 v[68:71], v7 offset:11264
	v_add_f32_e32 v86, v84, v85
	ds_read_b32 v82, v8 offset:12032
	ds_read_b128 v[76:79], v7 offset:11776
	v_add_f32_dpp v86, v86, v86 row_ror:8 row_mask:0xf bank_mask:0xf bound_ctrl:1
	v_pk_mul_f32 v[88:89], v[40:41], v[2:3]
	ds_read_b128 v[60:63], v7 offset:10752
	v_add_f32_dpp v86, v86, v86 row_ror:4 row_mask:0xf bank_mask:0xf bound_ctrl:1
	v_add_f32_e32 v101, v90, v91
	v_pk_mul_f32 v[92:93], v[42:43], v[0:1]
	v_add_f32_dpp v86, v86, v86 row_ror:2 row_mask:0xf bank_mask:0xf bound_ctrl:1
	v_pk_fma_f32 v[88:89], v[44:45], v[58:59], v[88:89] op_sel_hi:[1,0,1]
	ds_read_b128 v[24:27], v7 offset:12864
	v_add_f32_dpp v86, v86, v86 row_ror:1 row_mask:0xf bank_mask:0xf bound_ctrl:1
	v_pk_mul_f32 v[90:91], v[12:13], v[2:3]
	v_pk_fma_f32 v[92:93], v[46:47], v[58:59], v[92:93] op_sel_hi:[1,0,1]
	v_pk_fma_f32 v[2:3], v[52:53], v[86:87], v[88:89] op_sel_hi:[1,0,1]
	v_pk_fma_f32 v[90:91], v[14:15], v[0:1], v[90:91]
	v_pk_fma_f32 v[0:1], v[54:55], v[86:87], v[92:93] op_sel_hi:[1,0,1]
	s_waitcnt lgkmcnt(1)
	v_pk_mul_f32 v[84:85], v[72:73], v[2:3]
	ds_read_b128 v[16:19], v7 offset:12352
	v_pk_fma_f32 v[84:85], v[74:75], v[0:1], v[84:85]
	ds_read_b128 v[20:23], v7 offset:12608
	v_add_f32_e32 v86, v84, v85
	ds_read_b32 v34, v8 offset:13376
	ds_read_b128 v[28:31], v7 offset:13120
	v_add_f32_dpp v86, v86, v86 row_ror:8 row_mask:0xf bank_mask:0xf bound_ctrl:1
	v_pk_mul_f32 v[88:89], v[64:65], v[2:3]
	ds_read_b128 v[12:15], v7 offset:12096
	v_add_f32_dpp v86, v86, v86 row_ror:4 row_mask:0xf bank_mask:0xf bound_ctrl:1
	v_add_f32_e32 v102, v90, v91
	v_pk_mul_f32 v[92:93], v[66:67], v[0:1]
	v_add_f32_dpp v86, v86, v86 row_ror:2 row_mask:0xf bank_mask:0xf bound_ctrl:1
	v_pk_fma_f32 v[88:89], v[68:69], v[82:83], v[88:89] op_sel_hi:[1,0,1]
	ds_read_b128 v[48:51], v7 offset:14208
	v_add_f32_dpp v86, v86, v86 row_ror:1 row_mask:0xf bank_mask:0xf bound_ctrl:1
	v_pk_mul_f32 v[90:91], v[36:37], v[2:3]
	v_pk_fma_f32 v[92:93], v[70:71], v[82:83], v[92:93] op_sel_hi:[1,0,1]
	v_pk_fma_f32 v[2:3], v[76:77], v[86:87], v[88:89] op_sel_hi:[1,0,1]
	v_pk_fma_f32 v[90:91], v[38:39], v[0:1], v[90:91]
	v_pk_fma_f32 v[0:1], v[78:79], v[86:87], v[92:93] op_sel_hi:[1,0,1]
	s_waitcnt lgkmcnt(1)
	v_pk_mul_f32 v[84:85], v[24:25], v[2:3]
	ds_read_b128 v[40:43], v7 offset:13696
	v_pk_fma_f32 v[84:85], v[26:27], v[0:1], v[84:85]
	ds_read_b128 v[44:47], v7 offset:13952
	v_add_f32_e32 v86, v84, v85
	ds_read_b32 v58, v8 offset:14720
	ds_read_b128 v[52:55], v7 offset:14464
	v_add_f32_dpp v86, v86, v86 row_ror:8 row_mask:0xf bank_mask:0xf bound_ctrl:1
	v_pk_mul_f32 v[88:89], v[16:17], v[2:3]
	ds_read_b128 v[36:39], v7 offset:13440
	v_add_f32_dpp v86, v86, v86 row_ror:4 row_mask:0xf bank_mask:0xf bound_ctrl:1
	v_add_f32_e32 v103, v90, v91
	v_pk_mul_f32 v[92:93], v[18:19], v[0:1]
	v_add_f32_dpp v86, v86, v86 row_ror:2 row_mask:0xf bank_mask:0xf bound_ctrl:1
	v_pk_fma_f32 v[88:89], v[20:21], v[34:35], v[88:89] op_sel_hi:[1,0,1]
	ds_read_b128 v[72:75], v7 offset:15552
	v_add_f32_dpp v86, v86, v86 row_ror:1 row_mask:0xf bank_mask:0xf bound_ctrl:1
	v_pk_mul_f32 v[90:91], v[60:61], v[2:3]
	v_pk_fma_f32 v[92:93], v[22:23], v[34:35], v[92:93] op_sel_hi:[1,0,1]
	v_pk_fma_f32 v[2:3], v[28:29], v[86:87], v[88:89] op_sel_hi:[1,0,1]
	v_pk_fma_f32 v[90:91], v[62:63], v[0:1], v[90:91]
	v_pk_fma_f32 v[0:1], v[30:31], v[86:87], v[92:93] op_sel_hi:[1,0,1]
	s_waitcnt lgkmcnt(1)
	v_pk_mul_f32 v[84:85], v[48:49], v[2:3]
	ds_read_b128 v[64:67], v7 offset:15040
	v_pk_fma_f32 v[84:85], v[50:51], v[0:1], v[84:85]
	ds_read_b128 v[68:71], v7 offset:15296
	v_add_f32_e32 v86, v84, v85
	ds_read_b32 v82, v8 offset:16064
	ds_read_b128 v[76:79], v7 offset:15808
	v_add_f32_dpp v86, v86, v86 row_ror:8 row_mask:0xf bank_mask:0xf bound_ctrl:1
	v_pk_mul_f32 v[88:89], v[40:41], v[2:3]
	ds_read_b128 v[60:63], v7 offset:14784
	v_add_f32_dpp v86, v86, v86 row_ror:4 row_mask:0xf bank_mask:0xf bound_ctrl:1
	v_add_f32_e32 v104, v90, v91
	v_pk_mul_f32 v[92:93], v[42:43], v[0:1]
	v_add_f32_dpp v86, v86, v86 row_ror:2 row_mask:0xf bank_mask:0xf bound_ctrl:1
	v_pk_fma_f32 v[88:89], v[44:45], v[58:59], v[88:89] op_sel_hi:[1,0,1]
	ds_read_b128 v[24:27], v7 offset:16896
	v_add_f32_dpp v86, v86, v86 row_ror:1 row_mask:0xf bank_mask:0xf bound_ctrl:1
	v_pk_mul_f32 v[90:91], v[12:13], v[2:3]
	v_pk_fma_f32 v[92:93], v[46:47], v[58:59], v[92:93] op_sel_hi:[1,0,1]
	v_pk_fma_f32 v[2:3], v[52:53], v[86:87], v[88:89] op_sel_hi:[1,0,1]
	v_pk_fma_f32 v[90:91], v[14:15], v[0:1], v[90:91]
	v_pk_fma_f32 v[0:1], v[54:55], v[86:87], v[92:93] op_sel_hi:[1,0,1]
	s_waitcnt lgkmcnt(1)
	v_pk_mul_f32 v[84:85], v[72:73], v[2:3]
	ds_read_b128 v[16:19], v7 offset:16384
	v_pk_fma_f32 v[84:85], v[74:75], v[0:1], v[84:85]
	ds_read_b128 v[20:23], v7 offset:16640
	v_add_f32_e32 v86, v84, v85
	ds_read_b32 v34, v8 offset:17408
	ds_read_b128 v[28:31], v7 offset:17152
	v_add_f32_dpp v86, v86, v86 row_ror:8 row_mask:0xf bank_mask:0xf bound_ctrl:1
	v_pk_mul_f32 v[88:89], v[64:65], v[2:3]
	ds_read_b128 v[12:15], v7 offset:16128
	v_add_f32_dpp v86, v86, v86 row_ror:4 row_mask:0xf bank_mask:0xf bound_ctrl:1
	v_add_f32_e32 v105, v90, v91
	v_pk_mul_f32 v[92:93], v[66:67], v[0:1]
	v_add_f32_dpp v86, v86, v86 row_ror:2 row_mask:0xf bank_mask:0xf bound_ctrl:1
	v_pk_fma_f32 v[88:89], v[68:69], v[82:83], v[88:89] op_sel_hi:[1,0,1]
	ds_read_b128 v[48:51], v7 offset:18240
	v_add_f32_dpp v86, v86, v86 row_ror:1 row_mask:0xf bank_mask:0xf bound_ctrl:1
	v_pk_mul_f32 v[90:91], v[36:37], v[2:3]
	v_pk_fma_f32 v[92:93], v[70:71], v[82:83], v[92:93] op_sel_hi:[1,0,1]
	v_pk_fma_f32 v[2:3], v[76:77], v[86:87], v[88:89] op_sel_hi:[1,0,1]
	v_pk_fma_f32 v[90:91], v[38:39], v[0:1], v[90:91]
	v_pk_fma_f32 v[0:1], v[78:79], v[86:87], v[92:93] op_sel_hi:[1,0,1]
	s_waitcnt lgkmcnt(1)
	v_pk_mul_f32 v[84:85], v[24:25], v[2:3]
	ds_read_b128 v[40:43], v7 offset:17728
	v_pk_fma_f32 v[84:85], v[26:27], v[0:1], v[84:85]
	ds_read_b128 v[44:47], v7 offset:17984
	v_add_f32_e32 v86, v84, v85
	ds_read_b32 v58, v8 offset:18752
	ds_read_b128 v[52:55], v7 offset:18496
	v_add_f32_dpp v86, v86, v86 row_ror:8 row_mask:0xf bank_mask:0xf bound_ctrl:1
	v_pk_mul_f32 v[88:89], v[16:17], v[2:3]
	ds_read_b128 v[36:39], v7 offset:17472
	v_add_f32_dpp v86, v86, v86 row_ror:4 row_mask:0xf bank_mask:0xf bound_ctrl:1
	v_add_f32_e32 v106, v90, v91
	v_pk_mul_f32 v[92:93], v[18:19], v[0:1]
	v_add_f32_dpp v86, v86, v86 row_ror:2 row_mask:0xf bank_mask:0xf bound_ctrl:1
	v_pk_fma_f32 v[88:89], v[20:21], v[34:35], v[88:89] op_sel_hi:[1,0,1]
	ds_read_b128 v[72:75], v7 offset:19584
	v_add_f32_dpp v86, v86, v86 row_ror:1 row_mask:0xf bank_mask:0xf bound_ctrl:1
	v_pk_mul_f32 v[90:91], v[60:61], v[2:3]
	v_pk_fma_f32 v[92:93], v[22:23], v[34:35], v[92:93] op_sel_hi:[1,0,1]
	v_pk_fma_f32 v[2:3], v[28:29], v[86:87], v[88:89] op_sel_hi:[1,0,1]
	v_pk_fma_f32 v[90:91], v[62:63], v[0:1], v[90:91]
	v_pk_fma_f32 v[0:1], v[30:31], v[86:87], v[92:93] op_sel_hi:[1,0,1]
	s_waitcnt lgkmcnt(1)
	v_pk_mul_f32 v[84:85], v[48:49], v[2:3]
	ds_read_b128 v[64:67], v7 offset:19072
	v_pk_fma_f32 v[84:85], v[50:51], v[0:1], v[84:85]
	ds_read_b128 v[68:71], v7 offset:19328
	v_add_f32_e32 v86, v84, v85
	ds_read_b32 v82, v8 offset:20096
	ds_read_b128 v[76:79], v7 offset:19840
	v_add_f32_dpp v86, v86, v86 row_ror:8 row_mask:0xf bank_mask:0xf bound_ctrl:1
	v_pk_mul_f32 v[88:89], v[40:41], v[2:3]
	ds_read_b128 v[60:63], v7 offset:18816
	v_add_f32_dpp v86, v86, v86 row_ror:4 row_mask:0xf bank_mask:0xf bound_ctrl:1
	v_add_f32_e32 v107, v90, v91
	v_pk_mul_f32 v[92:93], v[42:43], v[0:1]
	v_add_f32_dpp v86, v86, v86 row_ror:2 row_mask:0xf bank_mask:0xf bound_ctrl:1
	v_pk_fma_f32 v[88:89], v[44:45], v[58:59], v[88:89] op_sel_hi:[1,0,1]
	ds_read_b128 v[24:27], v7 offset:20928
	v_add_f32_dpp v86, v86, v86 row_ror:1 row_mask:0xf bank_mask:0xf bound_ctrl:1
	v_pk_mul_f32 v[90:91], v[12:13], v[2:3]
	v_pk_fma_f32 v[92:93], v[46:47], v[58:59], v[92:93] op_sel_hi:[1,0,1]
	v_pk_fma_f32 v[2:3], v[52:53], v[86:87], v[88:89] op_sel_hi:[1,0,1]
	v_pk_fma_f32 v[90:91], v[14:15], v[0:1], v[90:91]
	v_pk_fma_f32 v[0:1], v[54:55], v[86:87], v[92:93] op_sel_hi:[1,0,1]
	s_waitcnt lgkmcnt(1)
	v_pk_mul_f32 v[84:85], v[72:73], v[2:3]
	ds_read_b128 v[16:19], v7 offset:20416
	v_pk_fma_f32 v[84:85], v[74:75], v[0:1], v[84:85]
	ds_read_b128 v[20:23], v7 offset:20672
	v_add_f32_e32 v86, v84, v85
	ds_read_b32 v34, v8 offset:21440
	ds_read_b128 v[28:31], v7 offset:21184
	v_add_f32_dpp v86, v86, v86 row_ror:8 row_mask:0xf bank_mask:0xf bound_ctrl:1
	v_pk_mul_f32 v[88:89], v[64:65], v[2:3]
	v_add_f32_e32 v108, v90, v91
	v_add_f32_dpp v86, v86, v86 row_ror:4 row_mask:0xf bank_mask:0xf bound_ctrl:1
	ds_read_b128 v[12:15], v7 offset:20160
	v_pk_mul_f32 v[92:93], v[66:67], v[0:1]
	v_add_f32_dpp v86, v86, v86 row_ror:2 row_mask:0xf bank_mask:0xf bound_ctrl:1
	v_pk_fma_f32 v[88:89], v[68:69], v[82:83], v[88:89] op_sel_hi:[1,0,1]
	v_pk_mul_f32 v[90:91], v[36:37], v[2:3]
	v_add_f32_dpp v86, v86, v86 row_ror:1 row_mask:0xf bank_mask:0xf bound_ctrl:1
	v_pk_fma_f32 v[92:93], v[70:71], v[82:83], v[92:93] op_sel_hi:[1,0,1]
	v_pk_fma_f32 v[2:3], v[76:77], v[86:87], v[88:89] op_sel_hi:[1,0,1]
	v_pk_fma_f32 v[90:91], v[38:39], v[0:1], v[90:91]
	ds_read_b128 v[48:51], v7 offset:22272
	v_pk_fma_f32 v[0:1], v[78:79], v[86:87], v[92:93] op_sel_hi:[1,0,1]
	s_waitcnt lgkmcnt(1)
	v_pk_mul_f32 v[84:85], v[24:25], v[2:3]
	ds_read_b128 v[40:43], v7 offset:21760
	v_pk_fma_f32 v[84:85], v[26:27], v[0:1], v[84:85]
	v_add_f32_e32 v109, v90, v91
	v_add_f32_e32 v86, v84, v85
	ds_read_b128 v[44:47], v7 offset:22016
	v_pk_mul_f32 v[88:89], v[16:17], v[2:3]
	v_add_f32_dpp v86, v86, v86 row_ror:8 row_mask:0xf bank_mask:0xf bound_ctrl:1
	ds_read_b32 v58, v8 offset:22784
	v_pk_mul_f32 v[90:91], v[60:61], v[2:3]
	v_add_f32_dpp v86, v86, v86 row_ror:4 row_mask:0xf bank_mask:0xf bound_ctrl:1
	v_pk_mul_f32 v[92:93], v[18:19], v[0:1]
	v_pk_fma_f32 v[88:89], v[20:21], v[34:35], v[88:89] op_sel_hi:[1,0,1]
	v_add_f32_dpp v86, v86, v86 row_ror:2 row_mask:0xf bank_mask:0xf bound_ctrl:1
	ds_read_b128 v[52:55], v7 offset:22528
	v_pk_fma_f32 v[90:91], v[62:63], v[0:1], v[90:91]
	v_add_f32_dpp v86, v86, v86 row_ror:1 row_mask:0xf bank_mask:0xf bound_ctrl:1
	ds_read_b128 v[36:39], v7 offset:21504
	v_pk_fma_f32 v[92:93], v[22:23], v[34:35], v[92:93] op_sel_hi:[1,0,1]
	v_pk_fma_f32 v[2:3], v[28:29], v[86:87], v[88:89] op_sel_hi:[1,0,1]
	v_add_f32_dpp v96, v96, v96 row_ror:8 row_mask:0xf bank_mask:0xf bound_ctrl:1
	v_add_f32_e32 v110, v90, v91
	ds_read_b128 v[72:75], v7 offset:23616
	v_add_f32_dpp v97, v97, v97 row_ror:8 row_mask:0xf bank_mask:0xf bound_ctrl:1
	v_pk_fma_f32 v[0:1], v[30:31], v[86:87], v[92:93] op_sel_hi:[1,0,1]
	v_pk_mul_f32 v[90:91], v[12:13], v[2:3]
	v_add_f32_dpp v98, v98, v98 row_ror:8 row_mask:0xf bank_mask:0xf bound_ctrl:1
	v_add_f32_dpp v96, v104, v104 row_ror:8 row_mask:0xf bank_mask:0xc
	v_add_f32_dpp v99, v99, v99 row_ror:8 row_mask:0xf bank_mask:0xf bound_ctrl:1
	v_add_f32_dpp v100, v100, v100 row_ror:8 row_mask:0xf bank_mask:0xf bound_ctrl:1
	v_pk_fma_f32 v[90:91], v[14:15], v[0:1], v[90:91]
	v_add_f32_dpp v97, v105, v105 row_ror:8 row_mask:0xf bank_mask:0xc
	v_add_f32_dpp v101, v101, v101 row_ror:8 row_mask:0xf bank_mask:0xf bound_ctrl:1
	s_waitcnt lgkmcnt(1)
	v_pk_mul_f32 v[84:85], v[48:49], v[2:3]
	v_add_f32_dpp v98, v106, v106 row_ror:8 row_mask:0xf bank_mask:0xc
	v_add_f32_dpp v102, v102, v102 row_ror:8 row_mask:0xf bank_mask:0xf bound_ctrl:1
	v_add_f32_e32 v111, v90, v91
	v_add_f32_dpp v99, v107, v107 row_ror:8 row_mask:0xf bank_mask:0xc
	v_add_f32_dpp v100, v108, v108 row_ror:8 row_mask:0xf bank_mask:0xc
	v_add_f32_dpp v103, v103, v103 row_ror:8 row_mask:0xf bank_mask:0xf bound_ctrl:1
	v_add_f32_dpp v96, v96, v96 row_ror:4 row_mask:0xf bank_mask:0xf bound_ctrl:1
	v_pk_fma_f32 v[84:85], v[50:51], v[0:1], v[84:85]
	v_add_f32_dpp v101, v109, v109 row_ror:8 row_mask:0xf bank_mask:0xc
	v_add_f32_dpp v97, v97, v97 row_ror:4 row_mask:0xf bank_mask:0xf bound_ctrl:1
	v_add_f32_dpp v102, v110, v110 row_ror:8 row_mask:0xf bank_mask:0xc
	v_add_f32_dpp v98, v98, v98 row_ror:4 row_mask:0xf bank_mask:0xf bound_ctrl:1
	v_add_f32_e32 v86, v84, v85
	v_add_f32_dpp v103, v111, v111 row_ror:8 row_mask:0xf bank_mask:0xc
	v_add_f32_dpp v96, v100, v100 row_ror:12 row_mask:0xf bank_mask:0x5
	v_add_f32_dpp v99, v99, v99 row_ror:4 row_mask:0xf bank_mask:0xf bound_ctrl:1
	v_add_f32_dpp v97, v101, v101 row_ror:12 row_mask:0xf bank_mask:0x5
	v_add_f32_dpp v98, v102, v102 row_ror:12 row_mask:0xf bank_mask:0x5
	ds_read_b128 v[64:67], v7 offset:23104
	v_add_f32_dpp v86, v86, v86 row_ror:8 row_mask:0xf bank_mask:0xf bound_ctrl:1
	v_add_f32_dpp v99, v103, v103 row_ror:12 row_mask:0xf bank_mask:0x5
	v_add_f32_dpp v96, v96, v96 quad_perm:[2,3,0,1] row_mask:0xf bank_mask:0xf bound_ctrl:1
	ds_read_b128 v[68:71], v7 offset:23360
	v_add_f32_dpp v97, v97, v97 quad_perm:[2,3,0,1] row_mask:0xf bank_mask:0xf bound_ctrl:1
	ds_read_b32 v82, v8 offset:24128
	v_add_f32_dpp v98, v98, v98 quad_perm:[2,3,0,1] row_mask:0xf bank_mask:0xf bound_ctrl:1
	ds_read_b128 v[76:79], v7 offset:23872
	v_add_f32_dpp v86, v86, v86 row_ror:4 row_mask:0xf bank_mask:0xf bound_ctrl:1
	v_add_f32_dpp v99, v99, v99 quad_perm:[2,3,0,1] row_mask:0xf bank_mask:0xf bound_ctrl:1
	v_add_f32_dpp v96, v96, v96 quad_perm:[1,0,3,2] row_mask:0xf bank_mask:0xf bound_ctrl:1
	ds_read_b128 v[60:63], v7 offset:22848
	v_add_f32_dpp v97, v97, v97 quad_perm:[1,0,3,2] row_mask:0xf bank_mask:0xf bound_ctrl:1
	v_add_f32_dpp v98, v98, v98 quad_perm:[1,0,3,2] row_mask:0xf bank_mask:0xf bound_ctrl:1
	ds_write_b32 v6, v96 offset:0
	v_add_f32_dpp v86, v86, v86 row_ror:2 row_mask:0xf bank_mask:0xf bound_ctrl:1
	v_add_f32_dpp v99, v99, v99 quad_perm:[1,0,3,2] row_mask:0xf bank_mask:0xf bound_ctrl:1
	ds_write_b32 v6, v97 offset:64
	v_pk_mul_f32 v[88:89], v[40:41], v[2:3]
	ds_write_b32 v6, v98 offset:128
	ds_write_b32 v6, v99 offset:192
	v_add_f32_dpp v86, v86, v86 row_ror:1 row_mask:0xf bank_mask:0xf bound_ctrl:1
	v_pk_mul_f32 v[92:93], v[42:43], v[0:1]
	v_pk_fma_f32 v[88:89], v[44:45], v[58:59], v[88:89] op_sel_hi:[1,0,1]
	ds_read_b128 v[24:27], v7 offset:24960
	v_pk_fma_f32 v[92:93], v[46:47], v[58:59], v[92:93] op_sel_hi:[1,0,1]
	v_pk_fma_f32 v[2:3], v[52:53], v[86:87], v[88:89] op_sel_hi:[1,0,1]
	v_pk_fma_f32 v[0:1], v[54:55], v[86:87], v[92:93] op_sel_hi:[1,0,1]
	s_waitcnt lgkmcnt(5)
	v_pk_mul_f32 v[84:85], v[72:73], v[2:3]
	ds_read_b128 v[16:19], v7 offset:24448
	v_pk_fma_f32 v[84:85], v[74:75], v[0:1], v[84:85]
	ds_read_b128 v[20:23], v7 offset:24704
	v_add_f32_e32 v86, v84, v85
	ds_read_b32 v34, v8 offset:25472
	ds_read_b128 v[28:31], v7 offset:25216
	v_add_f32_dpp v86, v86, v86 row_ror:8 row_mask:0xf bank_mask:0xf bound_ctrl:1
	v_pk_mul_f32 v[88:89], v[64:65], v[2:3]
	ds_read_b128 v[12:15], v7 offset:24192
	v_add_f32_dpp v86, v86, v86 row_ror:4 row_mask:0xf bank_mask:0xf bound_ctrl:1
	v_pk_mul_f32 v[92:93], v[66:67], v[0:1]
	v_pk_fma_f32 v[88:89], v[68:69], v[82:83], v[88:89] op_sel_hi:[1,0,1]
	v_add_f32_dpp v86, v86, v86 row_ror:2 row_mask:0xf bank_mask:0xf bound_ctrl:1
	ds_read_b128 v[48:51], v7 offset:26304
	v_pk_mul_f32 v[90:91], v[36:37], v[2:3]
	v_add_f32_dpp v86, v86, v86 row_ror:1 row_mask:0xf bank_mask:0xf bound_ctrl:1
	v_pk_fma_f32 v[92:93], v[70:71], v[82:83], v[92:93] op_sel_hi:[1,0,1]
	v_pk_fma_f32 v[2:3], v[76:77], v[86:87], v[88:89] op_sel_hi:[1,0,1]
	v_pk_fma_f32 v[90:91], v[38:39], v[0:1], v[90:91]
	v_pk_fma_f32 v[0:1], v[78:79], v[86:87], v[92:93] op_sel_hi:[1,0,1]
	s_waitcnt lgkmcnt(1)
	v_pk_mul_f32 v[84:85], v[24:25], v[2:3]
	ds_read_b128 v[40:43], v7 offset:25792
	v_pk_fma_f32 v[84:85], v[26:27], v[0:1], v[84:85]
	ds_read_b128 v[44:47], v7 offset:26048
	v_add_f32_e32 v86, v84, v85
	ds_read_b32 v58, v8 offset:26816
	ds_read_b128 v[52:55], v7 offset:26560
	v_add_f32_dpp v86, v86, v86 row_ror:8 row_mask:0xf bank_mask:0xf bound_ctrl:1
	v_pk_mul_f32 v[88:89], v[16:17], v[2:3]
	ds_read_b128 v[36:39], v7 offset:25536
	v_add_f32_dpp v86, v86, v86 row_ror:4 row_mask:0xf bank_mask:0xf bound_ctrl:1
	v_add_f32_e32 v112, v90, v91
	v_pk_mul_f32 v[92:93], v[18:19], v[0:1]
	v_add_f32_dpp v86, v86, v86 row_ror:2 row_mask:0xf bank_mask:0xf bound_ctrl:1
	v_pk_fma_f32 v[88:89], v[20:21], v[34:35], v[88:89] op_sel_hi:[1,0,1]
	ds_read_b128 v[72:75], v7 offset:27648
	v_add_f32_dpp v86, v86, v86 row_ror:1 row_mask:0xf bank_mask:0xf bound_ctrl:1
	v_pk_mul_f32 v[90:91], v[60:61], v[2:3]
	v_pk_fma_f32 v[92:93], v[22:23], v[34:35], v[92:93] op_sel_hi:[1,0,1]
	v_pk_fma_f32 v[2:3], v[28:29], v[86:87], v[88:89] op_sel_hi:[1,0,1]
	v_pk_fma_f32 v[90:91], v[62:63], v[0:1], v[90:91]
	v_pk_fma_f32 v[0:1], v[30:31], v[86:87], v[92:93] op_sel_hi:[1,0,1]
	s_waitcnt lgkmcnt(1)
	v_pk_mul_f32 v[84:85], v[48:49], v[2:3]
	ds_read_b128 v[64:67], v7 offset:27136
	v_pk_fma_f32 v[84:85], v[50:51], v[0:1], v[84:85]
	ds_read_b128 v[68:71], v7 offset:27392
	v_add_f32_e32 v86, v84, v85
	ds_read_b32 v82, v8 offset:28160
	ds_read_b128 v[76:79], v7 offset:27904
	v_add_f32_dpp v86, v86, v86 row_ror:8 row_mask:0xf bank_mask:0xf bound_ctrl:1
	v_pk_mul_f32 v[88:89], v[40:41], v[2:3]
	ds_read_b128 v[60:63], v7 offset:26880
	v_add_f32_dpp v86, v86, v86 row_ror:4 row_mask:0xf bank_mask:0xf bound_ctrl:1
	v_add_f32_e32 v113, v90, v91
	v_pk_mul_f32 v[92:93], v[42:43], v[0:1]
	v_add_f32_dpp v86, v86, v86 row_ror:2 row_mask:0xf bank_mask:0xf bound_ctrl:1
	v_pk_fma_f32 v[88:89], v[44:45], v[58:59], v[88:89] op_sel_hi:[1,0,1]
	ds_read_b128 v[24:27], v7 offset:28992
	v_add_f32_dpp v86, v86, v86 row_ror:1 row_mask:0xf bank_mask:0xf bound_ctrl:1
	v_pk_mul_f32 v[90:91], v[12:13], v[2:3]
	v_pk_fma_f32 v[92:93], v[46:47], v[58:59], v[92:93] op_sel_hi:[1,0,1]
	v_pk_fma_f32 v[2:3], v[52:53], v[86:87], v[88:89] op_sel_hi:[1,0,1]
	v_pk_fma_f32 v[90:91], v[14:15], v[0:1], v[90:91]
	v_pk_fma_f32 v[0:1], v[54:55], v[86:87], v[92:93] op_sel_hi:[1,0,1]
	s_waitcnt lgkmcnt(1)
	v_pk_mul_f32 v[84:85], v[72:73], v[2:3]
	ds_read_b128 v[16:19], v7 offset:28480
	v_pk_fma_f32 v[84:85], v[74:75], v[0:1], v[84:85]
	ds_read_b128 v[20:23], v7 offset:28736
	v_add_f32_e32 v86, v84, v85
	ds_read_b32 v34, v8 offset:29504
	ds_read_b128 v[28:31], v7 offset:29248
	v_add_f32_dpp v86, v86, v86 row_ror:8 row_mask:0xf bank_mask:0xf bound_ctrl:1
	v_pk_mul_f32 v[88:89], v[64:65], v[2:3]
	ds_read_b128 v[12:15], v7 offset:28224
	v_add_f32_dpp v86, v86, v86 row_ror:4 row_mask:0xf bank_mask:0xf bound_ctrl:1
	v_add_f32_e32 v114, v90, v91
	v_pk_mul_f32 v[92:93], v[66:67], v[0:1]
	v_add_f32_dpp v86, v86, v86 row_ror:2 row_mask:0xf bank_mask:0xf bound_ctrl:1
	v_pk_fma_f32 v[88:89], v[68:69], v[82:83], v[88:89] op_sel_hi:[1,0,1]
	ds_read_b128 v[48:51], v7 offset:30336
	v_add_f32_dpp v86, v86, v86 row_ror:1 row_mask:0xf bank_mask:0xf bound_ctrl:1
	v_pk_mul_f32 v[90:91], v[36:37], v[2:3]
	v_pk_fma_f32 v[92:93], v[70:71], v[82:83], v[92:93] op_sel_hi:[1,0,1]
	v_pk_fma_f32 v[2:3], v[76:77], v[86:87], v[88:89] op_sel_hi:[1,0,1]
	v_pk_fma_f32 v[90:91], v[38:39], v[0:1], v[90:91]
	v_pk_fma_f32 v[0:1], v[78:79], v[86:87], v[92:93] op_sel_hi:[1,0,1]
	s_waitcnt lgkmcnt(1)
	v_pk_mul_f32 v[84:85], v[24:25], v[2:3]
	ds_read_b128 v[40:43], v7 offset:29824
	v_pk_fma_f32 v[84:85], v[26:27], v[0:1], v[84:85]
	ds_read_b128 v[44:47], v7 offset:30080
	v_add_f32_e32 v86, v84, v85
	ds_read_b32 v58, v8 offset:30848
	ds_read_b128 v[52:55], v7 offset:30592
	v_add_f32_dpp v86, v86, v86 row_ror:8 row_mask:0xf bank_mask:0xf bound_ctrl:1
	v_pk_mul_f32 v[88:89], v[16:17], v[2:3]
	ds_read_b128 v[36:39], v7 offset:29568
	v_add_f32_dpp v86, v86, v86 row_ror:4 row_mask:0xf bank_mask:0xf bound_ctrl:1
	v_add_f32_e32 v115, v90, v91
	v_pk_mul_f32 v[92:93], v[18:19], v[0:1]
	v_add_f32_dpp v86, v86, v86 row_ror:2 row_mask:0xf bank_mask:0xf bound_ctrl:1
	v_pk_fma_f32 v[88:89], v[20:21], v[34:35], v[88:89] op_sel_hi:[1,0,1]
	ds_read_b128 v[72:75], v7 offset:31680
	v_add_f32_dpp v86, v86, v86 row_ror:1 row_mask:0xf bank_mask:0xf bound_ctrl:1
	v_pk_mul_f32 v[90:91], v[60:61], v[2:3]
	v_pk_fma_f32 v[92:93], v[22:23], v[34:35], v[92:93] op_sel_hi:[1,0,1]
	v_pk_fma_f32 v[2:3], v[28:29], v[86:87], v[88:89] op_sel_hi:[1,0,1]
	v_pk_fma_f32 v[90:91], v[62:63], v[0:1], v[90:91]
	v_pk_fma_f32 v[0:1], v[30:31], v[86:87], v[92:93] op_sel_hi:[1,0,1]
	s_waitcnt lgkmcnt(1)
	v_pk_mul_f32 v[84:85], v[48:49], v[2:3]
	ds_read_b128 v[64:67], v7 offset:31168
	v_pk_fma_f32 v[84:85], v[50:51], v[0:1], v[84:85]
	ds_read_b128 v[68:71], v7 offset:31424
	v_add_f32_e32 v86, v84, v85
	ds_read_b32 v82, v8 offset:32192
	ds_read_b128 v[76:79], v7 offset:31936
	v_add_f32_dpp v86, v86, v86 row_ror:8 row_mask:0xf bank_mask:0xf bound_ctrl:1
	v_pk_mul_f32 v[88:89], v[40:41], v[2:3]
	ds_read_b128 v[60:63], v7 offset:30912
	v_add_f32_dpp v86, v86, v86 row_ror:4 row_mask:0xf bank_mask:0xf bound_ctrl:1
	v_add_f32_e32 v116, v90, v91
	v_pk_mul_f32 v[92:93], v[42:43], v[0:1]
	v_add_f32_dpp v86, v86, v86 row_ror:2 row_mask:0xf bank_mask:0xf bound_ctrl:1
	v_pk_fma_f32 v[88:89], v[44:45], v[58:59], v[88:89] op_sel_hi:[1,0,1]
	ds_read_b128 v[24:27], v7 offset:33024
	v_add_f32_dpp v86, v86, v86 row_ror:1 row_mask:0xf bank_mask:0xf bound_ctrl:1
	v_pk_mul_f32 v[90:91], v[12:13], v[2:3]
	v_pk_fma_f32 v[92:93], v[46:47], v[58:59], v[92:93] op_sel_hi:[1,0,1]
	v_pk_fma_f32 v[2:3], v[52:53], v[86:87], v[88:89] op_sel_hi:[1,0,1]
	v_pk_fma_f32 v[90:91], v[14:15], v[0:1], v[90:91]
	v_pk_fma_f32 v[0:1], v[54:55], v[86:87], v[92:93] op_sel_hi:[1,0,1]
	s_waitcnt lgkmcnt(1)
	v_pk_mul_f32 v[84:85], v[72:73], v[2:3]
	ds_read_b128 v[16:19], v7 offset:32512
	v_pk_fma_f32 v[84:85], v[74:75], v[0:1], v[84:85]
	ds_read_b128 v[20:23], v7 offset:32768
	v_add_f32_e32 v86, v84, v85
	ds_read_b32 v34, v8 offset:33536
	ds_read_b128 v[28:31], v7 offset:33280
	v_add_f32_dpp v86, v86, v86 row_ror:8 row_mask:0xf bank_mask:0xf bound_ctrl:1
	v_pk_mul_f32 v[88:89], v[64:65], v[2:3]
	ds_read_b128 v[12:15], v7 offset:32256
	v_add_f32_dpp v86, v86, v86 row_ror:4 row_mask:0xf bank_mask:0xf bound_ctrl:1
	v_add_f32_e32 v117, v90, v91
	v_pk_mul_f32 v[92:93], v[66:67], v[0:1]
	v_add_f32_dpp v86, v86, v86 row_ror:2 row_mask:0xf bank_mask:0xf bound_ctrl:1
	v_pk_fma_f32 v[88:89], v[68:69], v[82:83], v[88:89] op_sel_hi:[1,0,1]
	ds_read_b128 v[48:51], v7 offset:34368
	v_add_f32_dpp v86, v86, v86 row_ror:1 row_mask:0xf bank_mask:0xf bound_ctrl:1
	v_pk_mul_f32 v[90:91], v[36:37], v[2:3]
	v_pk_fma_f32 v[92:93], v[70:71], v[82:83], v[92:93] op_sel_hi:[1,0,1]
	v_pk_fma_f32 v[2:3], v[76:77], v[86:87], v[88:89] op_sel_hi:[1,0,1]
	v_pk_fma_f32 v[90:91], v[38:39], v[0:1], v[90:91]
	v_pk_fma_f32 v[0:1], v[78:79], v[86:87], v[92:93] op_sel_hi:[1,0,1]
	s_waitcnt lgkmcnt(1)
	v_pk_mul_f32 v[84:85], v[24:25], v[2:3]
	ds_read_b128 v[40:43], v7 offset:33856
	v_pk_fma_f32 v[84:85], v[26:27], v[0:1], v[84:85]
	ds_read_b128 v[44:47], v7 offset:34112
	v_add_f32_e32 v86, v84, v85
	ds_read_b32 v58, v8 offset:34880
	ds_read_b128 v[52:55], v7 offset:34624
	v_add_f32_dpp v86, v86, v86 row_ror:8 row_mask:0xf bank_mask:0xf bound_ctrl:1
	v_pk_mul_f32 v[88:89], v[16:17], v[2:3]
	ds_read_b128 v[36:39], v7 offset:33600
	v_add_f32_dpp v86, v86, v86 row_ror:4 row_mask:0xf bank_mask:0xf bound_ctrl:1
	v_add_f32_e32 v118, v90, v91
	v_pk_mul_f32 v[92:93], v[18:19], v[0:1]
	v_add_f32_dpp v86, v86, v86 row_ror:2 row_mask:0xf bank_mask:0xf bound_ctrl:1
	v_pk_fma_f32 v[88:89], v[20:21], v[34:35], v[88:89] op_sel_hi:[1,0,1]
	ds_read_b128 v[72:75], v7 offset:35712
	v_add_f32_dpp v86, v86, v86 row_ror:1 row_mask:0xf bank_mask:0xf bound_ctrl:1
	v_pk_mul_f32 v[90:91], v[60:61], v[2:3]
	v_pk_fma_f32 v[92:93], v[22:23], v[34:35], v[92:93] op_sel_hi:[1,0,1]
	v_pk_fma_f32 v[2:3], v[28:29], v[86:87], v[88:89] op_sel_hi:[1,0,1]
	v_pk_fma_f32 v[90:91], v[62:63], v[0:1], v[90:91]
	v_pk_fma_f32 v[0:1], v[30:31], v[86:87], v[92:93] op_sel_hi:[1,0,1]
	s_waitcnt lgkmcnt(1)
	v_pk_mul_f32 v[84:85], v[48:49], v[2:3]
	ds_read_b128 v[64:67], v7 offset:35200
	v_pk_fma_f32 v[84:85], v[50:51], v[0:1], v[84:85]
	ds_read_b128 v[68:71], v7 offset:35456
	v_add_f32_e32 v86, v84, v85
	ds_read_b32 v82, v8 offset:36224
	ds_read_b128 v[76:79], v7 offset:35968
	v_add_f32_dpp v86, v86, v86 row_ror:8 row_mask:0xf bank_mask:0xf bound_ctrl:1
	v_pk_mul_f32 v[88:89], v[40:41], v[2:3]
	ds_read_b128 v[60:63], v7 offset:34944
	v_add_f32_dpp v86, v86, v86 row_ror:4 row_mask:0xf bank_mask:0xf bound_ctrl:1
	v_add_f32_e32 v119, v90, v91
	v_pk_mul_f32 v[92:93], v[42:43], v[0:1]
	v_add_f32_dpp v86, v86, v86 row_ror:2 row_mask:0xf bank_mask:0xf bound_ctrl:1
	v_pk_fma_f32 v[88:89], v[44:45], v[58:59], v[88:89] op_sel_hi:[1,0,1]
	ds_read_b128 v[24:27], v7 offset:37056
	v_add_f32_dpp v86, v86, v86 row_ror:1 row_mask:0xf bank_mask:0xf bound_ctrl:1
	v_pk_mul_f32 v[90:91], v[12:13], v[2:3]
	v_pk_fma_f32 v[92:93], v[46:47], v[58:59], v[92:93] op_sel_hi:[1,0,1]
	v_pk_fma_f32 v[2:3], v[52:53], v[86:87], v[88:89] op_sel_hi:[1,0,1]
	v_pk_fma_f32 v[90:91], v[14:15], v[0:1], v[90:91]
	v_pk_fma_f32 v[0:1], v[54:55], v[86:87], v[92:93] op_sel_hi:[1,0,1]
	s_waitcnt lgkmcnt(1)
	v_pk_mul_f32 v[84:85], v[72:73], v[2:3]
	ds_read_b128 v[16:19], v7 offset:36544
	v_pk_fma_f32 v[84:85], v[74:75], v[0:1], v[84:85]
	ds_read_b128 v[20:23], v7 offset:36800
	v_add_f32_e32 v86, v84, v85
	ds_read_b32 v34, v8 offset:37568
	ds_read_b128 v[28:31], v7 offset:37312
	v_add_f32_dpp v86, v86, v86 row_ror:8 row_mask:0xf bank_mask:0xf bound_ctrl:1
	v_pk_mul_f32 v[88:89], v[64:65], v[2:3]
	ds_read_b128 v[12:15], v7 offset:36288
	v_add_f32_dpp v86, v86, v86 row_ror:4 row_mask:0xf bank_mask:0xf bound_ctrl:1
	v_add_f32_e32 v104, v90, v91
	v_pk_mul_f32 v[92:93], v[66:67], v[0:1]
	v_add_f32_dpp v86, v86, v86 row_ror:2 row_mask:0xf bank_mask:0xf bound_ctrl:1
	v_pk_fma_f32 v[88:89], v[68:69], v[82:83], v[88:89] op_sel_hi:[1,0,1]
	ds_read_b128 v[48:51], v7 offset:38400
	v_add_f32_dpp v86, v86, v86 row_ror:1 row_mask:0xf bank_mask:0xf bound_ctrl:1
	v_pk_mul_f32 v[90:91], v[36:37], v[2:3]
	v_pk_fma_f32 v[92:93], v[70:71], v[82:83], v[92:93] op_sel_hi:[1,0,1]
	v_pk_fma_f32 v[2:3], v[76:77], v[86:87], v[88:89] op_sel_hi:[1,0,1]
	v_pk_fma_f32 v[90:91], v[38:39], v[0:1], v[90:91]
	v_pk_fma_f32 v[0:1], v[78:79], v[86:87], v[92:93] op_sel_hi:[1,0,1]
	s_waitcnt lgkmcnt(1)
	v_pk_mul_f32 v[84:85], v[24:25], v[2:3]
	ds_read_b128 v[40:43], v7 offset:37888
	v_pk_fma_f32 v[84:85], v[26:27], v[0:1], v[84:85]
	ds_read_b128 v[44:47], v7 offset:38144
	v_add_f32_e32 v86, v84, v85
	ds_read_b32 v58, v8 offset:38912
	ds_read_b128 v[52:55], v7 offset:38656
	v_add_f32_dpp v86, v86, v86 row_ror:8 row_mask:0xf bank_mask:0xf bound_ctrl:1
	v_pk_mul_f32 v[88:89], v[16:17], v[2:3]
	ds_read_b128 v[36:39], v7 offset:37632
	v_add_f32_dpp v86, v86, v86 row_ror:4 row_mask:0xf bank_mask:0xf bound_ctrl:1
	v_add_f32_e32 v105, v90, v91
	v_pk_mul_f32 v[92:93], v[18:19], v[0:1]
	v_add_f32_dpp v86, v86, v86 row_ror:2 row_mask:0xf bank_mask:0xf bound_ctrl:1
	v_pk_fma_f32 v[88:89], v[20:21], v[34:35], v[88:89] op_sel_hi:[1,0,1]
	ds_read_b128 v[72:75], v7 offset:39744
	v_add_f32_dpp v86, v86, v86 row_ror:1 row_mask:0xf bank_mask:0xf bound_ctrl:1
	v_pk_mul_f32 v[90:91], v[60:61], v[2:3]
	v_pk_fma_f32 v[92:93], v[22:23], v[34:35], v[92:93] op_sel_hi:[1,0,1]
	v_pk_fma_f32 v[2:3], v[28:29], v[86:87], v[88:89] op_sel_hi:[1,0,1]
	v_pk_fma_f32 v[90:91], v[62:63], v[0:1], v[90:91]
	v_pk_fma_f32 v[0:1], v[30:31], v[86:87], v[92:93] op_sel_hi:[1,0,1]
	s_waitcnt lgkmcnt(1)
	v_pk_mul_f32 v[84:85], v[48:49], v[2:3]
	ds_read_b128 v[64:67], v7 offset:39232
	v_pk_fma_f32 v[84:85], v[50:51], v[0:1], v[84:85]
	ds_read_b128 v[68:71], v7 offset:39488
	v_add_f32_e32 v86, v84, v85
	ds_read_b32 v82, v8 offset:40256
	ds_read_b128 v[76:79], v7 offset:40000
	v_add_f32_dpp v86, v86, v86 row_ror:8 row_mask:0xf bank_mask:0xf bound_ctrl:1
	v_pk_mul_f32 v[88:89], v[40:41], v[2:3]
	ds_read_b128 v[60:63], v7 offset:38976
	v_add_f32_dpp v86, v86, v86 row_ror:4 row_mask:0xf bank_mask:0xf bound_ctrl:1
	v_add_f32_e32 v106, v90, v91
	v_pk_mul_f32 v[92:93], v[42:43], v[0:1]
	v_add_f32_dpp v86, v86, v86 row_ror:2 row_mask:0xf bank_mask:0xf bound_ctrl:1
	v_pk_fma_f32 v[88:89], v[44:45], v[58:59], v[88:89] op_sel_hi:[1,0,1]
	ds_read_b128 v[24:27], v7 offset:41088
	v_add_f32_dpp v86, v86, v86 row_ror:1 row_mask:0xf bank_mask:0xf bound_ctrl:1
	v_pk_mul_f32 v[90:91], v[12:13], v[2:3]
	v_pk_fma_f32 v[92:93], v[46:47], v[58:59], v[92:93] op_sel_hi:[1,0,1]
	v_pk_fma_f32 v[2:3], v[52:53], v[86:87], v[88:89] op_sel_hi:[1,0,1]
	v_pk_fma_f32 v[90:91], v[14:15], v[0:1], v[90:91]
	v_pk_fma_f32 v[0:1], v[54:55], v[86:87], v[92:93] op_sel_hi:[1,0,1]
	s_waitcnt lgkmcnt(1)
	v_pk_mul_f32 v[84:85], v[72:73], v[2:3]
	ds_read_b128 v[16:19], v7 offset:40576
	v_pk_fma_f32 v[84:85], v[74:75], v[0:1], v[84:85]
	ds_read_b128 v[20:23], v7 offset:40832
	v_add_f32_e32 v86, v84, v85
	ds_read_b32 v34, v8 offset:41600
	ds_read_b128 v[28:31], v7 offset:41344
	v_add_f32_dpp v86, v86, v86 row_ror:8 row_mask:0xf bank_mask:0xf bound_ctrl:1
	v_pk_mul_f32 v[88:89], v[64:65], v[2:3]
	ds_read_b128 v[12:15], v7 offset:40320
	v_add_f32_dpp v86, v86, v86 row_ror:4 row_mask:0xf bank_mask:0xf bound_ctrl:1
	v_add_f32_e32 v107, v90, v91
	v_pk_mul_f32 v[92:93], v[66:67], v[0:1]
	v_add_f32_dpp v86, v86, v86 row_ror:2 row_mask:0xf bank_mask:0xf bound_ctrl:1
	v_pk_fma_f32 v[88:89], v[68:69], v[82:83], v[88:89] op_sel_hi:[1,0,1]
	ds_read_b128 v[48:51], v7 offset:42432
	v_add_f32_dpp v86, v86, v86 row_ror:1 row_mask:0xf bank_mask:0xf bound_ctrl:1
	v_pk_mul_f32 v[90:91], v[36:37], v[2:3]
	v_pk_fma_f32 v[92:93], v[70:71], v[82:83], v[92:93] op_sel_hi:[1,0,1]
	v_pk_fma_f32 v[2:3], v[76:77], v[86:87], v[88:89] op_sel_hi:[1,0,1]
	v_pk_fma_f32 v[90:91], v[38:39], v[0:1], v[90:91]
	v_pk_fma_f32 v[0:1], v[78:79], v[86:87], v[92:93] op_sel_hi:[1,0,1]
	s_waitcnt lgkmcnt(1)
	v_pk_mul_f32 v[84:85], v[24:25], v[2:3]
	ds_read_b128 v[40:43], v7 offset:41920
	v_pk_fma_f32 v[84:85], v[26:27], v[0:1], v[84:85]
	ds_read_b128 v[44:47], v7 offset:42176
	v_add_f32_e32 v86, v84, v85
	ds_read_b32 v58, v8 offset:42944
	ds_read_b128 v[52:55], v7 offset:42688
	v_add_f32_dpp v86, v86, v86 row_ror:8 row_mask:0xf bank_mask:0xf bound_ctrl:1
	v_pk_mul_f32 v[88:89], v[16:17], v[2:3]
	v_add_f32_e32 v108, v90, v91
	v_add_f32_dpp v86, v86, v86 row_ror:4 row_mask:0xf bank_mask:0xf bound_ctrl:1
	ds_read_b128 v[36:39], v7 offset:41664
	v_pk_mul_f32 v[92:93], v[18:19], v[0:1]
	v_add_f32_dpp v86, v86, v86 row_ror:2 row_mask:0xf bank_mask:0xf bound_ctrl:1
	v_pk_fma_f32 v[88:89], v[20:21], v[34:35], v[88:89] op_sel_hi:[1,0,1]
	v_pk_mul_f32 v[90:91], v[60:61], v[2:3]
	v_add_f32_dpp v86, v86, v86 row_ror:1 row_mask:0xf bank_mask:0xf bound_ctrl:1
	v_pk_fma_f32 v[92:93], v[22:23], v[34:35], v[92:93] op_sel_hi:[1,0,1]
	v_pk_fma_f32 v[2:3], v[28:29], v[86:87], v[88:89] op_sel_hi:[1,0,1]
	v_pk_fma_f32 v[90:91], v[62:63], v[0:1], v[90:91]
	v_pk_fma_f32 v[0:1], v[30:31], v[86:87], v[92:93] op_sel_hi:[1,0,1]
	s_waitcnt lgkmcnt(0)
	v_pk_mul_f32 v[84:85], v[48:49], v[2:3]
	v_add_f32_e32 v109, v90, v91
	v_pk_fma_f32 v[84:85], v[50:51], v[0:1], v[84:85]
	v_pk_mul_f32 v[90:91], v[12:13], v[2:3]
	v_add_f32_e32 v86, v84, v85
	v_pk_mul_f32 v[88:89], v[40:41], v[2:3]
	v_pk_mul_f32 v[92:93], v[42:43], v[0:1]
	v_add_f32_dpp v86, v86, v86 row_ror:8 row_mask:0xf bank_mask:0xf bound_ctrl:1
	v_pk_fma_f32 v[88:89], v[44:45], v[58:59], v[88:89] op_sel_hi:[1,0,1]
	v_pk_fma_f32 v[90:91], v[14:15], v[0:1], v[90:91]
	v_add_f32_dpp v86, v86, v86 row_ror:4 row_mask:0xf bank_mask:0xf bound_ctrl:1
	v_pk_fma_f32 v[92:93], v[46:47], v[58:59], v[92:93] op_sel_hi:[1,0,1]
	v_add_f32_dpp v112, v112, v112 row_ror:8 row_mask:0xf bank_mask:0xf bound_ctrl:1
	v_add_f32_dpp v86, v86, v86 row_ror:2 row_mask:0xf bank_mask:0xf bound_ctrl:1
	v_add_f32_e32 v110, v90, v91
	v_add_f32_dpp v113, v113, v113 row_ror:8 row_mask:0xf bank_mask:0xf bound_ctrl:1
	v_add_f32_dpp v86, v86, v86 row_ror:1 row_mask:0xf bank_mask:0xf bound_ctrl:1
	v_add_f32_dpp v114, v114, v114 row_ror:8 row_mask:0xf bank_mask:0xf bound_ctrl:1
	v_pk_fma_f32 v[2:3], v[52:53], v[86:87], v[88:89] op_sel_hi:[1,0,1]
	v_pk_fma_f32 v[0:1], v[54:55], v[86:87], v[92:93] op_sel_hi:[1,0,1]
	v_pk_mul_f32 v[90:91], v[36:37], v[2:3]
	v_add_f32_dpp v112, v104, v104 row_ror:8 row_mask:0xf bank_mask:0xc
	v_add_f32_dpp v115, v115, v115 row_ror:8 row_mask:0xf bank_mask:0xf bound_ctrl:1
	v_add_f32_dpp v116, v116, v116 row_ror:8 row_mask:0xf bank_mask:0xf bound_ctrl:1
	v_pk_fma_f32 v[90:91], v[38:39], v[0:1], v[90:91]
	v_add_f32_dpp v113, v105, v105 row_ror:8 row_mask:0xf bank_mask:0xc
	v_add_f32_dpp v117, v117, v117 row_ror:8 row_mask:0xf bank_mask:0xf bound_ctrl:1
	v_add_f32_dpp v114, v106, v106 row_ror:8 row_mask:0xf bank_mask:0xc
	v_add_f32_dpp v118, v118, v118 row_ror:8 row_mask:0xf bank_mask:0xf bound_ctrl:1
	v_add_f32_e32 v111, v90, v91
	v_add_f32_dpp v115, v107, v107 row_ror:8 row_mask:0xf bank_mask:0xc
	v_add_f32_dpp v116, v108, v108 row_ror:8 row_mask:0xf bank_mask:0xc
	v_add_f32_dpp v119, v119, v119 row_ror:8 row_mask:0xf bank_mask:0xf bound_ctrl:1
	v_add_f32_dpp v112, v112, v112 row_ror:4 row_mask:0xf bank_mask:0xf bound_ctrl:1
	v_add_f32_dpp v117, v109, v109 row_ror:8 row_mask:0xf bank_mask:0xc
	v_add_f32_dpp v113, v113, v113 row_ror:4 row_mask:0xf bank_mask:0xf bound_ctrl:1
	v_add_f32_dpp v118, v110, v110 row_ror:8 row_mask:0xf bank_mask:0xc
	v_add_f32_dpp v114, v114, v114 row_ror:4 row_mask:0xf bank_mask:0xf bound_ctrl:1
	v_add_f32_dpp v119, v111, v111 row_ror:8 row_mask:0xf bank_mask:0xc
	v_add_f32_dpp v112, v116, v116 row_ror:12 row_mask:0xf bank_mask:0x5
	v_add_f32_dpp v115, v115, v115 row_ror:4 row_mask:0xf bank_mask:0xf bound_ctrl:1
	v_add_f32_dpp v113, v117, v117 row_ror:12 row_mask:0xf bank_mask:0x5
	v_add_f32_dpp v114, v118, v118 row_ror:12 row_mask:0xf bank_mask:0x5
	v_add_f32_dpp v115, v119, v119 row_ror:12 row_mask:0xf bank_mask:0x5
	v_add_f32_dpp v112, v112, v112 quad_perm:[2,3,0,1] row_mask:0xf bank_mask:0xf bound_ctrl:1
	v_add_f32_dpp v113, v113, v113 quad_perm:[2,3,0,1] row_mask:0xf bank_mask:0xf bound_ctrl:1
	v_add_f32_dpp v114, v114, v114 quad_perm:[2,3,0,1] row_mask:0xf bank_mask:0xf bound_ctrl:1
	v_add_f32_dpp v115, v115, v115 quad_perm:[2,3,0,1] row_mask:0xf bank_mask:0xf bound_ctrl:1
	v_add_f32_dpp v112, v112, v112 quad_perm:[1,0,3,2] row_mask:0xf bank_mask:0xf bound_ctrl:1
	v_add_f32_dpp v113, v113, v113 quad_perm:[1,0,3,2] row_mask:0xf bank_mask:0xf bound_ctrl:1
	v_add_f32_dpp v114, v114, v114 quad_perm:[1,0,3,2] row_mask:0xf bank_mask:0xf bound_ctrl:1
	ds_write_b32 v6, v112 offset:1024
	v_add_f32_dpp v115, v115, v115 quad_perm:[1,0,3,2] row_mask:0xf bank_mask:0xf bound_ctrl:1
	ds_write_b32 v6, v113 offset:1088
	ds_write_b32 v6, v114 offset:1152
	ds_write_b32 v6, v115 offset:1216
	s_add_i32 s13, s13, 1
	s_cmpk_eq_i32 s13, 0x80
	s_cbranch_scc0 .Lscan_chunk
	s_waitcnt lgkmcnt(0)
	s_barrier
	s_branch .LBB0_189
